# first mixer phase: the second pooling item pair of the eight workgroups with seven neighbourhood-attention query rows moves to eight lightly loaded workgroups
# speedup vs baseline: 1.0132x; 1.0132x over previous
.LBB0_204:
	s_andn2_b64 vcc, exec, s[0:1]
	s_cbranch_vccnz .LBB0_349
	s_and_b64 s[0:1], s[50:51], exec
	s_movk_i32 s0, 0x410
	s_cselect_b32 s16, s0, 0x400
	s_mov_b32 s3, -1
	v_readlane_b32 s2, v252, 2
	s_cmp_eq_u32 s2, 0x100
	s_cbranch_scc0 .Lpl_done
	v_readlane_b32 s2, v254, 58
	s_and_b32 s12, s2, -2
	s_cmp_eq_u32 s12, 64
	s_cbranch_scc1 .Lpl_heavy
	s_cmp_eq_u32 s12, 0x7c
	s_cbranch_scc1 .Lpl_heavy
	s_cmp_eq_u32 s12, 0xbe
	s_cbranch_scc1 .Lpl_heavy
	s_cmp_eq_u32 s12, 0xfa
	s_cbranch_scc1 .Lpl_heavy
	s_sub_u32 s12, s2, 0x7e
	s_cmp_lt_u32 s12, 8
	s_cbranch_scc0 .Lpl_done
	s_lshr_b32 s13, s12, 1
	s_and_b32 s12, s12, 1
	s_movk_i32 s3, 64
	s_cmp_eq_u32 s13, 1
	s_cselect_b32 s3, 0x7c, s3
	s_cmp_eq_u32 s13, 2
	s_cselect_b32 s3, 0xbe, s3
	s_cmp_eq_u32 s13, 3
	s_cselect_b32 s3, 0xfa, s3
	s_add_i32 s3, s3, s12
	s_lshl_b32 s3, s3, 1
	s_addk_i32 s3, 0x200
	s_branch .Lpl_done
.Lpl_heavy:
	s_movk_i32 s16, 0x200
.Lpl_done:
	s_nop 0
	v_writelane_b32 v255, s3, 23
	v_readlane_b32 s0, v254, 29
	v_mov_b32_e32 v156, v202
	s_cmp_ge_i32 s0, s16
	s_movk_i32 s18, 0x4100
	s_movk_i32 s19, 0x1000
	s_mov_b32 s40, 0x3fb8aa3b
	s_cbranch_scc1 .LBB0_232
	v_and_b32_e32 v2, 0xff, v156
	v_or_b32_e32 v4, 0x100, v2
	v_lshrrev_b32_e32 v33, 3, v4
	v_or_b32_e32 v4, 0x200, v2
	s_movk_i32 s0, 0x280
	v_cmp_gt_u32_e32 vcc, s0, v4
	v_ashrrev_i32_e32 v23, 8, v156
	s_mov_b32 s14, 0xa000
	v_cndmask_b32_e32 v2, v2, v4, vcc
	v_lshrrev_b32_e32 v34, 3, v2
	v_lshlrev_b32_e32 v2, 2, v156
	v_and_b32_e32 v6, 60, v2
	v_bfe_u32 v32, v156, 3, 5
	v_lshrrev_b32_e32 v2, 3, v4
	v_mul_u32_u24_e32 v4, 0x48, v6
	v_mad_i32_i24 v0, v23, s14, 0
	v_and_b32_e32 v7, 30, v32
	v_lshlrev_b32_e32 v4, 1, v4
	v_mul_u32_u24_e32 v11, 0x104, v2
	v_add3_u32 v35, v0, v7, v4
	v_and_b32_e32 v7, 62, v33
	v_and_b32_e32 v2, 0x5e, v2
	v_lshlrev_b32_e32 v3, 3, v156
	v_add3_u32 v36, v0, v7, v4
	v_add3_u32 v37, v0, v2, v4
	v_and_b32_e32 v12, 63, v156
	v_lshrrev_b32_e32 v4, 2, v156
	v_and_b32_e32 v3, 56, v3
	v_and_b32_e32 v38, 48, v4
	v_lshlrev_b32_e32 v13, 2, v12
	v_and_b32_e32 v39, 15, v156
	v_and_b32_e32 v2, 48, v156
	v_lshl_add_u32 v8, v3, 2, v0
	v_add_u32_e32 v22, v0, v13
	v_or_b32_e32 v7, v38, v39
	v_add_u32_e32 v0, v0, v2
	s_movk_i32 s0, 0x90
	v_mad_u32_u24 v40, v7, s0, v0
	s_lshl_b64 s[0:1], s[62:63], 10
	s_lshl_b64 s[2:3], s[62:63], 16
	v_readlane_b32 s60, v254, 7
	v_mul_u32_u24_e32 v7, 0x48, v39
	v_readlane_b32 s61, v254, 8
	s_add_u32 s2, s60, s2
	v_readlane_b32 s12, v252, 28
	v_lshl_add_u32 v41, v7, 1, v0
	v_readlane_b32 s62, v254, 9
	s_addc_u32 s3, s61, s3
	v_lshlrev_b32_e32 v0, 1, v3
	v_readlane_b32 s13, v252, 29
	v_readlane_b32 s63, v254, 10
	s_add_u32 s0, s62, s0
	v_lshl_add_u64 v[24:25], s[12:13], 0, v[0:1]
	v_lshlrev_b32_e32 v0, 2, v6
	v_lshl_add_u64 v[6:7], s[2:3], 0, v[0:1]
	v_lshlrev_b32_e32 v0, 4, v156
	s_addc_u32 s1, s63, s1
	v_mov_b32_e32 v3, v1
	v_mul_i32_i24_e32 v5, 0xa000, v23
	v_and_b32_e32 v0, 0xf00, v0
	v_lshl_add_u64 v[28:29], s[0:1], 0, v[2:3]
	v_bfe_u32 v2, v156, 6, 2
	v_lshl_add_u64 v[26:27], v[6:7], 0, v[0:1]
	v_or_b32_e32 v0, v5, v13
	v_readlane_b32 s0, v254, 32
	v_mul_u32_u24_e32 v3, 0x1040, v2
	v_mul_u32_u24_e32 v9, 0x104, v32
	v_add_u32_e32 v42, s0, v0
	v_add3_u32 v43, v0, v3, s0
	v_mul_u32_u24_e32 v0, 0x900, v2
	v_mad_i32_i24 v0, v23, s14, v0
	v_mul_u32_u24_e32 v10, 0x104, v33
	v_and_b32_e32 v4, 12, v4
	v_readlane_b32 s62, v255, 12
	v_lshl_or_b32 v0, v12, 1, v0
	v_readlane_b32 s0, v254, 33
	v_readlane_b32 s63, v255, 13
	v_add_u32_e32 v45, v8, v9
	v_add_u32_e32 v44, s0, v0
	v_add_u32_e32 v46, v8, v10
	v_add_u32_e32 v47, v8, v11
	v_lshlrev_b32_e32 v30, 1, v4
	v_readlane_b32 s17, v254, 29
	v_readlane_b32 s64, v254, 11
	v_readlane_b32 s65, v254, 12
	v_readlane_b32 s66, v254, 13
	v_readlane_b32 s67, v254, 14
	v_readlane_b32 s68, v254, 15
	v_readlane_b32 s69, v254, 16
	v_readlane_b32 s70, v254, 17
	v_readlane_b32 s71, v254, 18
	v_readlane_b32 s72, v254, 19
	v_readlane_b32 s73, v254, 20
	v_readlane_b32 s74, v254, 21
	v_readlane_b32 s75, v254, 22
	s_branch .LBB0_208
.LBB0_207:
	s_waitcnt lgkmcnt(0)
	s_barrier
	ds_read_b128 v[2:5], v40 offset:20800
	ds_read_b128 v[6:9], v41 offset:30016
	ds_read_b128 v[10:13], v41 offset:32320
	ds_read_b128 v[16:19], v41 offset:34624
	ds_read_b128 v[48:51], v41 offset:36928
	s_waitcnt lgkmcnt(3)
	v_mfma_f32_16x16x32_bf16 v[6:9], v[6:9], v[2:5], 0
	v_lshlrev_b32_e32 v0, 2, v15
	v_readlane_b32 s0, v252, 20
	v_readlane_b32 s1, v252, 21
	s_waitcnt lgkmcnt(2)
	v_mfma_f32_16x16x32_bf16 v[10:13], v[10:13], v[2:5], 0
	v_mov_b32_e32 v31, v1
	s_waitcnt lgkmcnt(1)
	v_mfma_f32_16x16x32_bf16 v[16:19], v[16:19], v[2:5], 0
	s_waitcnt lgkmcnt(0)
	v_mfma_f32_16x16x32_bf16 v[2:5], v[48:51], v[2:5], 0
	ds_read_b128 v[48:51], v40 offset:20864
	ds_read_b128 v[52:55], v41 offset:30080
	s_waitcnt lgkmcnt(0)
	v_mfma_f32_16x16x32_bf16 v[52:55], v[52:55], v[48:51], v[6:9]
	s_nop 2
	ds_read_b128 v[6:9], v41 offset:32384
	s_waitcnt lgkmcnt(0)
	v_mfma_f32_16x16x32_bf16 v[10:13], v[6:9], v[48:51], v[10:13]
	ds_read_b128 v[6:9], v41 offset:34688
	s_waitcnt lgkmcnt(0)
	v_mfma_f32_16x16x32_bf16 v[6:9], v[6:9], v[48:51], v[16:19]
	s_nop 2
	ds_read_b128 v[16:19], v41 offset:36992
	s_waitcnt lgkmcnt(0)
	v_mfma_f32_16x16x32_bf16 v[2:5], v[16:19], v[48:51], v[2:5]
	v_lshl_add_u64 v[18:19], v[28:29], 0, v[0:1]
	v_lshlrev_b32_e32 v0, 1, v15
	v_lshl_add_u64 v[16:17], s[0:1], 0, v[0:1]
	v_or_b32_e32 v0, v14, v39
	v_cmp_gt_i32_e64 s[0:1], s37, v0
	s_nop 1
	v_cndmask_b32_e64 v14, 3, 1, s[0:1]
	v_add_u32_e32 v14, v14, v0
	v_ashrrev_i32_e32 v15, 31, v14
	v_lshlrev_b64 v[14:15], 11, v[14:15]
	v_lshl_add_u64 v[14:15], v[16:17], 0, v[14:15]
	v_lshl_add_u64 v[20:21], v[14:15], 0, v[30:31]
	global_load_dwordx4 v[14:17], v[18:19], off
	v_readlane_b32 s0, v252, 7
	v_readlane_b32 s1, v252, 8
	s_waitcnt vmcnt(0)
	v_mul_f32_e32 v0, v52, v14
	v_mul_f32_e32 v14, v53, v15
	v_mul_f32_e32 v15, v54, v16
	v_mul_f32_e32 v16, v55, v17
	v_cvt_pk_bf16_f32 v14, v0, v14
	v_cvt_pk_bf16_f32 v15, v15, v16
	global_store_dwordx2 v[20:21], v[14:15], off
	global_load_dwordx4 v[14:17], v[18:19], off offset:64
	s_waitcnt vmcnt(0)
	v_mul_f32_e32 v0, v10, v14
	v_mul_f32_e32 v10, v11, v15
	v_mul_f32_e32 v11, v12, v16
	v_mul_f32_e32 v12, v13, v17
	v_cvt_pk_bf16_f32 v10, v0, v10
	v_cvt_pk_bf16_f32 v11, v11, v12
	global_store_dwordx2 v[20:21], v[10:11], off offset:32
	global_load_dwordx4 v[10:13], v[18:19], off offset:128
	s_waitcnt vmcnt(0)
	v_mul_f32_e32 v0, v6, v10
	v_mul_f32_e32 v6, v7, v11
	v_mul_f32_e32 v7, v8, v12
	v_mul_f32_e32 v8, v9, v13
	v_cvt_pk_bf16_f32 v6, v0, v6
	v_cvt_pk_bf16_f32 v7, v7, v8
	global_store_dwordx2 v[20:21], v[6:7], off offset:64
	global_load_dwordx4 v[6:9], v[18:19], off offset:192
	s_waitcnt vmcnt(0)
	v_mul_f32_e32 v0, v2, v6
	v_mul_f32_e32 v2, v3, v7
	v_mul_f32_e32 v3, v4, v8
	v_mul_f32_e32 v4, v5, v9
	v_cvt_pk_bf16_f32 v2, v0, v2
	v_cvt_pk_bf16_f32 v3, v3, v4
	global_store_dwordx2 v[20:21], v[2:3], off offset:96
	s_barrier
	s_load_dword s0, s[0:1], 0x10
	s_waitcnt lgkmcnt(0)
	s_lshr_b32 s0, s0, 16
	s_cmp_lg_u32 s0, 0
	s_cselect_b64 s[0:1], -1, 0
	s_cmp_lg_u64 s[0:1], 0
	v_readlane_b32 s0, v252, 2
	s_addc_u32 s0, s0, 0
	s_lshl_b32 s0, s0, 1
	s_add_i32 s17, s0, s17
	v_readlane_b32 s1, v252, 3
	s_cmp_ge_i32 s17, s16
	s_cbranch_scc0 .LBB0_208
	v_readlane_b32 s0, v255, 23
	s_cmp_lt_i32 s0, 0
	s_cbranch_scc1 .LBB0_232
	s_mov_b32 s17, s0
	s_mov_b32 s0, -1
	s_nop 0
	v_writelane_b32 v255, s0, 23
